# s5_prompt step 1 re-split over waves (one Win n-tile x two m-tiles per wave: half the Win fragment loads), on top of LRU prefetch placement and S5 blocked scan
# speedup vs baseline: 1.0024x; 1.0024x over previous
; #define LAS __attribute__((address_space(3)))
; __device__ __forceinline__ void s5_prompt(const Args& a, LAS unsigned char* lds, int b, int g, int tid, int lane, int wave) {
;     ...
;     {
;         const int mt = wave & 3, nt0 = (wave >> 2) * 2;
;         const bf16_t* w0 = Win + (size_t)(32 * nt0 + r32) * 256 + 8 * hh;
;         bf16x8 bw[2][16];
;         {
;             u32x4 v[8];
; #pragma unroll
;             for (int i = 0; i < 8; ++i) { const int q = tid + 512 * i, t = q >> 1, half = q & 1; v[i] = *(const u32x4*)(U + (size_t)(b * SEQ + t) * DH + 16 * g + 8 * half); }
; #pragma unroll
;             for (int ks = 0; ks < 16; ++ks) { bw[0][ks] = *(const bf16x8*)(w0 + 16 * ks); bw[1][ks] = *(const bf16x8*)(w0 + 32 * 256 + 16 * ks); }
;             asm volatile("" ::: "memory");
; #pragma unroll
;             for (int i = 0; i < 8; ++i) { const int q = tid + 512 * i, t = q >> 1, half = q & 1; *(LAS u32x4*)(XCs + (t >> 4) * S5_PITCH + (t & 15) * 32 + 16 * half) = v[i]; }
;         }
;         __syncthreads();
.LBB0_559:
	s_lshl_b32 s0, s35, 3
	s_and_b32 s0, s0, 56
	s_bfe_u32 s1, s35, 0x30003
	s_or_b32 s36, s0, s1
	s_lshl_b32 s0, s36, 18
	s_add_u32 s0, s13, s0
	s_addc_u32 s1, s28, 0
	s_add_u32 s6, s0, 0x10000
	s_addc_u32 s7, s1, 0
	s_lshl_b32 s37, s35, 5
	s_and_b32 s37, s37, 0xfffff800
	v_readlane_b32 s48, v254, 40
	v_readlane_b32 s49, v254, 41
	v_lshlrev_b32_e32 v34, 4, v0
	s_nop 3
	s_lshl_b32 s50, s37, 11
	s_lshl_b32 s51, s36, 16
	s_add_u32 s48, s48, s50
	s_addc_u32 s49, s49, 0
	s_add_u32 s48, s48, s51
	s_addc_u32 s49, s49, 0
	s_mul_i32 s44, s36, 0x2400
	v_or_b32_e32 v2, s37, v162
	v_or_b32_e32 v6, s37, v185
	v_or_b32_e32 v8, s37, v186
	v_or_b32_e32 v14, s37, v187
	v_or_b32_e32 v16, s37, v188
	v_or_b32_e32 v22, s37, v189
	v_or_b32_e32 v24, s37, v190
	v_lshl_add_u64 v[36:37], v[168:169], 0, s[44:45]
	s_lshl_b32 s44, s36, 5
	v_ashrrev_i32_e32 v3, 31, v2
	v_ashrrev_i32_e32 v7, 31, v6
	v_ashrrev_i32_e32 v9, 31, v8
	v_ashrrev_i32_e32 v15, 31, v14
	v_ashrrev_i32_e32 v17, 31, v16
	v_ashrrev_i32_e32 v23, 31, v22
	v_ashrrev_i32_e32 v25, 31, v24
	v_lshl_add_u64 v[30:31], v[172:173], 0, s[44:45]
	v_lshlrev_b64 v[2:3], 11, v[2:3]
	v_lshlrev_b64 v[6:7], 11, v[6:7]
	v_lshlrev_b64 v[8:9], 11, v[8:9]
	v_lshlrev_b64 v[14:15], 11, v[14:15]
	v_lshlrev_b64 v[16:17], 11, v[16:17]
	v_lshlrev_b64 v[22:23], 11, v[22:23]
	v_lshlrev_b64 v[24:25], 11, v[24:25]
	v_lshl_add_u64 v[2:3], v[30:31], 0, v[2:3]
	v_lshl_add_u64 v[6:7], v[30:31], 0, v[6:7]
	v_lshl_add_u64 v[10:11], v[30:31], 0, v[8:9]
	v_lshl_add_u64 v[14:15], v[30:31], 0, v[14:15]
	v_lshl_add_u64 v[18:19], v[30:31], 0, v[16:17]
	v_lshl_add_u64 v[22:23], v[30:31], 0, v[22:23]
	v_lshl_add_u64 v[26:27], v[30:31], 0, v[24:25]
	global_load_dwordx4 v[2:5], v34, s[48:49]
	s_nop 0
	s_add_u32 s48, s48, 0x2000
	s_addc_u32 s49, s49, 0
	global_load_dwordx4 v[6:9], v34, s[48:49]
	s_nop 0
	s_add_u32 s48, s48, 0x2000
	s_addc_u32 s49, s49, 0
	global_load_dwordx4 v[10:13], v34, s[48:49]
	s_nop 0
	s_add_u32 s48, s48, 0x2000
	s_addc_u32 s49, s49, 0
	global_load_dwordx4 v[14:17], v34, s[48:49]
	s_nop 0
	s_add_u32 s48, s48, 0x2000
	s_addc_u32 s49, s49, 0
	global_load_dwordx4 v[18:21], v34, s[48:49]
	s_nop 0
	s_add_u32 s48, s48, 0x2000
	s_addc_u32 s49, s49, 0
	global_load_dwordx4 v[22:25], v34, s[48:49]
	s_nop 0
	s_add_u32 s48, s48, 0x2000
	s_addc_u32 s49, s49, 0
	global_load_dwordx4 v[26:29], v34, s[48:49]
	v_or_b32_e32 v32, s37, v191
	v_ashrrev_i32_e32 v33, 31, v32
	v_lshlrev_b64 v[32:33], 11, v[32:33]
	v_lshl_add_u64 v[30:31], v[30:31], 0, v[32:33]
	s_add_u32 s48, s48, 0x2000
	s_addc_u32 s49, s49, 0
	global_load_dwordx4 v[30:33], v34, s[48:49]
	v_readlane_b32 s38, v254, 12
	s_lshr_b32 s38, s38, 6
	s_lshr_b32 s39, s38, 2
	s_lshl_b32 s39, s39, 1
	s_and_b32 s38, s38, 3
	s_sub_i32 s39, s39, s38
	s_lshl_b32 s38, s38, 14
	v_lshl_add_u32 v35, v210, 4, s38
	global_load_dword v34, v[36:37], off offset:512
	global_load_dword v36, v[36:37], off offset:768
	s_add_u32 s48, s0, 0x0
	s_addc_u32 s49, s1, 0
	global_load_dwordx4 v[38:41], v35, s[48:49]
	s_add_u32 s50, s0, 0x400
	s_addc_u32 s51, s1, 0
	global_load_dwordx4 v[42:45], v35, s[50:51]
	s_add_u32 s48, s0, 0x800
	s_addc_u32 s49, s1, 0
	global_load_dwordx4 v[46:49], v35, s[48:49]
	s_add_u32 s50, s0, 0xc00
	s_addc_u32 s51, s1, 0
	global_load_dwordx4 v[50:53], v35, s[50:51]
	s_add_u32 s48, s0, 0x1000
	s_addc_u32 s49, s1, 0
	global_load_dwordx4 v[54:57], v35, s[48:49]
	s_add_u32 s50, s0, 0x1400
	s_addc_u32 s51, s1, 0
	global_load_dwordx4 v[58:61], v35, s[50:51]
	s_mul_i32 s38, s39, 0x4200
	v_add_u32_e32 v118, s38, v207
	s_mul_i32 s38, s39, 0x4180
	v_add_u32_e32 v119, s38, v192
	s_andn2_b64 vcc, exec, s[68:69]
	s_waitcnt vmcnt(15)
	ds_write_b128 v199, v[2:5]
	s_waitcnt vmcnt(14)
	ds_write_b128 v200, v[6:9]
	s_waitcnt vmcnt(13)
	ds_write_b128 v201, v[10:13]
	s_waitcnt vmcnt(12)
	ds_write_b128 v202, v[14:17]
	s_waitcnt vmcnt(11)
	ds_write_b128 v203, v[18:21]
	s_waitcnt vmcnt(10)
	ds_write_b128 v204, v[22:25]
	s_waitcnt vmcnt(9)
	ds_write_b128 v205, v[26:29]
	s_waitcnt vmcnt(8)
	ds_write_b128 v206, v[30:33]
	s_waitcnt lgkmcnt(0)
	s_barrier
; #define LAS __attribute__((address_space(3)))
; #define MFMA32(a, b, c) __builtin_amdgcn_mfma_f32_32x32x16_bf16((a), (b), (c), 0, 0, 0)
; __device__ __forceinline__ void s5_prompt(const Args& a, LAS unsigned char* lds, int b, int g, int tid, int lane, int wave) {
;     ...
;         f32x16 acc0, acc1;
; #pragma unroll
;         for (int i = 0; i < 16; ++i) { acc0[i] = 0.f; acc1[i] = 0.f; }
;         const LAS unsigned char* xa = XCs + (32 * mt + r32) * S5_PITCH + 16 * hh;
; #pragma unroll
;         for (int ks = 0; ks < 16; ++ks) { const bf16x8 af = *(const LAS bf16x8*)(xa + 32 * ks); acc0 = MFMA32(af, bw[0][ks], acc0); acc1 = MFMA32(af, bw[1][ks], acc1); }
;         LAS float* Z = (LAS float*)ZS;
; #pragma unroll
;         for (int i = 0; i < 16; ++i) { const int j = 32 * mt + (i & 3) + 8 * (i >> 2) + 4 * hh;
;             Z[j * (S5_PITCH / 4) + 32 * nt0 + r32] = acc0[i]; Z[j * (S5_PITCH / 4) + 32 * nt0 + 32 + r32] = acc1[i]; }
;     }
	ds_read_b128 v[102:105], v118
	ds_read_b128 v[106:109], v118 offset:16896
	ds_read_b128 v[110:113], v118 offset:32
	ds_read_b128 v[114:117], v118 offset:16928
	s_waitcnt vmcnt(5) lgkmcnt(2)
	v_mfma_f32_32x32x16_bf16 v[2:17], v[102:105], v[38:41], 0
	v_mfma_f32_32x32x16_bf16 v[18:33], v[106:109], v[38:41], 0
	s_add_u32 s48, s0, 0x1800
	s_addc_u32 s49, s1, 0
	global_load_dwordx4 v[62:65], v35, s[48:49]
	ds_read_b128 v[102:105], v118 offset:64
	ds_read_b128 v[106:109], v118 offset:16960
	s_waitcnt vmcnt(5) lgkmcnt(2)
	v_mfma_f32_32x32x16_bf16 v[2:17], v[110:113], v[42:45], v[2:17]
	v_mfma_f32_32x32x16_bf16 v[18:33], v[114:117], v[42:45], v[18:33]
	s_add_u32 s50, s0, 0x1c00
	s_addc_u32 s51, s1, 0
	global_load_dwordx4 v[66:69], v35, s[50:51]
	ds_read_b128 v[110:113], v118 offset:96
	ds_read_b128 v[114:117], v118 offset:16992
	s_waitcnt vmcnt(5) lgkmcnt(2)
	v_mfma_f32_32x32x16_bf16 v[2:17], v[102:105], v[46:49], v[2:17]
	v_mfma_f32_32x32x16_bf16 v[18:33], v[106:109], v[46:49], v[18:33]
	s_add_u32 s48, s0, 0x2000
	s_addc_u32 s49, s1, 0
	global_load_dwordx4 v[70:73], v35, s[48:49]
	ds_read_b128 v[102:105], v118 offset:128
	ds_read_b128 v[106:109], v118 offset:17024
	s_waitcnt vmcnt(5) lgkmcnt(2)
	v_mfma_f32_32x32x16_bf16 v[2:17], v[110:113], v[50:53], v[2:17]
	v_mfma_f32_32x32x16_bf16 v[18:33], v[114:117], v[50:53], v[18:33]
	s_add_u32 s50, s0, 0x2400
	s_addc_u32 s51, s1, 0
	global_load_dwordx4 v[74:77], v35, s[50:51]
	ds_read_b128 v[110:113], v118 offset:160
	ds_read_b128 v[114:117], v118 offset:17056
	s_waitcnt vmcnt(5) lgkmcnt(2)
	v_mfma_f32_32x32x16_bf16 v[2:17], v[102:105], v[54:57], v[2:17]
	v_mfma_f32_32x32x16_bf16 v[18:33], v[106:109], v[54:57], v[18:33]
	s_add_u32 s48, s0, 0x2800
	s_addc_u32 s49, s1, 0
	global_load_dwordx4 v[78:81], v35, s[48:49]
	ds_read_b128 v[102:105], v118 offset:192
	ds_read_b128 v[106:109], v118 offset:17088
	s_waitcnt vmcnt(5) lgkmcnt(2)
	v_mfma_f32_32x32x16_bf16 v[2:17], v[110:113], v[58:61], v[2:17]
	v_mfma_f32_32x32x16_bf16 v[18:33], v[114:117], v[58:61], v[18:33]
	s_add_u32 s50, s0, 0x2c00
	s_addc_u32 s51, s1, 0
	global_load_dwordx4 v[82:85], v35, s[50:51]
	ds_read_b128 v[110:113], v118 offset:224
	ds_read_b128 v[114:117], v118 offset:17120
	s_waitcnt vmcnt(5) lgkmcnt(2)
	v_mfma_f32_32x32x16_bf16 v[2:17], v[102:105], v[62:65], v[2:17]
	v_mfma_f32_32x32x16_bf16 v[18:33], v[106:109], v[62:65], v[18:33]
	s_add_u32 s48, s0, 0x3000
	s_addc_u32 s49, s1, 0
	global_load_dwordx4 v[86:89], v35, s[48:49]
	ds_read_b128 v[102:105], v118 offset:256
	ds_read_b128 v[106:109], v118 offset:17152
	s_waitcnt vmcnt(5) lgkmcnt(2)
	v_mfma_f32_32x32x16_bf16 v[2:17], v[110:113], v[66:69], v[2:17]
	v_mfma_f32_32x32x16_bf16 v[18:33], v[114:117], v[66:69], v[18:33]
	s_add_u32 s50, s0, 0x3400
	s_addc_u32 s51, s1, 0
	global_load_dwordx4 v[90:93], v35, s[50:51]
	ds_read_b128 v[110:113], v118 offset:288
	ds_read_b128 v[114:117], v118 offset:17184
	s_waitcnt vmcnt(5) lgkmcnt(2)
	v_mfma_f32_32x32x16_bf16 v[2:17], v[102:105], v[70:73], v[2:17]
	v_mfma_f32_32x32x16_bf16 v[18:33], v[106:109], v[70:73], v[18:33]
	s_add_u32 s48, s0, 0x3800
	s_addc_u32 s49, s1, 0
	global_load_dwordx4 v[94:97], v35, s[48:49]
	ds_read_b128 v[102:105], v118 offset:320
	ds_read_b128 v[106:109], v118 offset:17216
	s_waitcnt vmcnt(5) lgkmcnt(2)
	v_mfma_f32_32x32x16_bf16 v[2:17], v[110:113], v[74:77], v[2:17]
	v_mfma_f32_32x32x16_bf16 v[18:33], v[114:117], v[74:77], v[18:33]
	s_add_u32 s50, s0, 0x3c00
	s_addc_u32 s51, s1, 0
	global_load_dwordx4 v[98:101], v35, s[50:51]
	ds_read_b128 v[110:113], v118 offset:352
	ds_read_b128 v[114:117], v118 offset:17248
	s_waitcnt vmcnt(5) lgkmcnt(2)
	v_mfma_f32_32x32x16_bf16 v[2:17], v[102:105], v[78:81], v[2:17]
	v_mfma_f32_32x32x16_bf16 v[18:33], v[106:109], v[78:81], v[18:33]
	ds_read_b128 v[102:105], v118 offset:384
	ds_read_b128 v[106:109], v118 offset:17280
	s_waitcnt vmcnt(4) lgkmcnt(2)
	v_mfma_f32_32x32x16_bf16 v[2:17], v[110:113], v[82:85], v[2:17]
	v_mfma_f32_32x32x16_bf16 v[18:33], v[114:117], v[82:85], v[18:33]
	ds_read_b128 v[110:113], v118 offset:416
	ds_read_b128 v[114:117], v118 offset:17312
	s_waitcnt vmcnt(3) lgkmcnt(2)
	v_mfma_f32_32x32x16_bf16 v[2:17], v[102:105], v[86:89], v[2:17]
	v_mfma_f32_32x32x16_bf16 v[18:33], v[106:109], v[86:89], v[18:33]
	ds_read_b128 v[102:105], v118 offset:448
	ds_read_b128 v[106:109], v118 offset:17344
	s_waitcnt vmcnt(2) lgkmcnt(2)
	v_mfma_f32_32x32x16_bf16 v[2:17], v[110:113], v[90:93], v[2:17]
	v_mfma_f32_32x32x16_bf16 v[18:33], v[114:117], v[90:93], v[18:33]
	ds_read_b128 v[110:113], v118 offset:480
	ds_read_b128 v[114:117], v118 offset:17376
	s_waitcnt vmcnt(1) lgkmcnt(2)
	v_mfma_f32_32x32x16_bf16 v[2:17], v[102:105], v[94:97], v[2:17]
	v_mfma_f32_32x32x16_bf16 v[18:33], v[106:109], v[94:97], v[18:33]
	s_waitcnt vmcnt(0) lgkmcnt(0)
	v_mfma_f32_32x32x16_bf16 v[2:17], v[110:113], v[98:101], v[2:17]
	v_mfma_f32_32x32x16_bf16 v[18:33], v[114:117], v[98:101], v[18:33]
	s_nop 11
	ds_write_b32 v119, v2
	ds_write_b32 v119, v18 offset:16896
	ds_write_b32 v119, v3 offset:528
	ds_write_b32 v119, v19 offset:17424
	ds_write_b32 v119, v4 offset:1056
	ds_write_b32 v119, v20 offset:17952
	ds_write_b32 v119, v5 offset:1584
	ds_write_b32 v119, v21 offset:18480
	ds_write_b32 v119, v6 offset:4224
	ds_write_b32 v119, v22 offset:21120
	ds_write_b32 v119, v7 offset:4752
	ds_write_b32 v119, v23 offset:21648
	ds_write_b32 v119, v8 offset:5280
	ds_write_b32 v119, v24 offset:22176
	ds_write_b32 v119, v9 offset:5808
	ds_write_b32 v119, v25 offset:22704
	s_waitcnt lgkmcnt(6)
	ds_write_b32 v119, v10 offset:8448
	ds_write_b32 v119, v26 offset:25344
	ds_write_b32 v119, v11 offset:8976
	ds_write_b32 v119, v27 offset:25872
	ds_write_b32 v119, v12 offset:9504
	ds_write_b32 v119, v28 offset:26400
	ds_write_b32 v119, v13 offset:10032
	ds_write_b32 v119, v29 offset:26928
	ds_write_b32 v119, v14 offset:12672
	ds_write_b32 v119, v30 offset:29568
	ds_write_b32 v119, v15 offset:13200
	ds_write_b32 v119, v31 offset:30096
	ds_write_b32 v119, v16 offset:13728
	ds_write_b32 v119, v32 offset:30624
	ds_write_b32 v119, v17 offset:14256
	ds_write_b32 v119, v33 offset:31152
	v_lshl_add_u64 v[2:3], s[6:7], 0, v[174:175]
	v_lshl_add_u64 v[2:3], v[2:3], 0, v[166:167]
	s_waitcnt lgkmcnt(0)
	s_barrier
	s_mov_b64 s[50:51], s[6:7]
	s_mul_i32 s48, s3, 0x6000
	s_add_u32 s48, s50, s48
	s_addc_u32 s49, s51, 0
	v_lshlrev_b32_e32 v225, 4, v210
	v_add_u32_e32 v226, 0x1000, v225
	v_add_u32_e32 v227, 0x2000, v225
	v_add_u32_e32 v228, 0x3000, v225
	v_add_u32_e32 v229, 0x4000, v225
	v_add_u32_e32 v230, 0x5000, v225
	global_load_dwordx4 v[66:69], v225, s[48:49]
	global_load_dwordx4 v[70:73], v225, s[48:49] offset:1024
	v_cndmask_b32_e64 v4, 0, 1, s[68:69]
	v_cmp_ne_u32_e64 s[0:1], 1, v4
	s_cbranch_vccnz .LBB0_561
	global_load_dwordx4 v[74:77], v225, s[48:49] offset:2048
	s_and_b64 vcc, exec, s[0:1]
	s_cbranch_vccnz .LBB0_563
	s_branch .LBB0_562
